# conv rows stored write-through (sc1); per-workgroup L2 write-back before the conv-done counter removed
# speedup vs baseline: 1.0548x; 1.0093x over previous
; __device__ __forceinline__ unsigned cvt_pk_bf16(float lo, float hi) { unsigned r; asm volatile("v_cvt_pk_bf16_f32 %0, %1, %2" : "=v"(r) : "v"(lo), "v"(hi)); return r; }
; __device__ __forceinline__ void conv_block(ArgP a, int layer, int r0, int lane, const bf16* U, bf16* BG) {
;     ...
;         for (int k = 0; k < 4; ++k) {
;             float u0[8], bg[8], y[8];
;             { const u32x4 w = uw[k]; u0[0] = bflo(w.x); u0[1] = bfhi(w.x); u0[2] = bflo(w.y); u0[3] = bfhi(w.y); u0[4] = bflo(w.z); u0[5] = bfhi(w.z); u0[6] = bflo(w.w); u0[7] = bfhi(w.w); }
;             { const u32x4 w = bw[k]; bg[0] = bflo(w.x); bg[1] = bfhi(w.x); bg[2] = bflo(w.y); bg[3] = bfhi(w.y); bg[4] = bflo(w.z); bg[5] = bfhi(w.z); bg[6] = bflo(w.w); bg[7] = bfhi(w.w); }
; #pragma unroll
;             for (int x = 0; x < 8; ++x) y[x] = bg[x] * (w0[x] * p2[x] + w1[x] * p1[x] + w2[x] * u0[x]);
;             u32x4 wv; wv.x = cvt_pk_bf16(y[0], y[1]); wv.y = cvt_pk_bf16(y[2], y[3]); wv.z = cvt_pk_bf16(y[4], y[5]); wv.w = cvt_pk_bf16(y[6], y[7]);
;             *(u32x4*)(BG + (size_t)(r0 + k) * DM + col) = wv;
;             if (st_out && k >= 2) { float* so = st_out + (size_t)(k - 2) * DM + col; *(f32x4*)so = (f32x4){u0[0], u0[1], u0[2], u0[3]}; *(f32x4*)(so + 4) = (f32x4){u0[4], u0[5], u0[6], u0[7]}; }
; #pragma unroll
;             for (int x = 0; x < 8; ++x) { p2[x] = p1[x]; p1[x] = u0[x]; }
;         }
.LBB0_501:
	s_or_b64 exec, exec, s[26:27]
	s_waitcnt vmcnt(13)
	v_lshlrev_b32_e32 v101, 16, v32
	s_waitcnt vmcnt(11)
	v_lshlrev_b32_e32 v17, 16, v68
	v_and_b32_e32 v19, 0xffff0000, v68
	v_lshlrev_b32_e32 v21, 16, v69
	v_and_b32_e32 v23, 0xffff0000, v69
	s_waitcnt vmcnt(0)
	v_mov_b32_e32 v68, v60
	v_mov_b32_e32 v69, v56
	v_lshlrev_b32_e32 v105, 16, v64
	v_and_b32_e32 v107, 0xffff0000, v64
	v_lshlrev_b32_e32 v132, 16, v65
	v_and_b32_e32 v133, 0xffff0000, v65
	v_mov_b32_e32 v64, v101
	v_mov_b32_e32 v65, v4
	v_pk_mul_f32 v[64:65], v[68:69], v[64:65]
	v_lshlrev_b32_e32 v100, 16, v36
	v_fma_f32 v4, v52, v16, v65
	v_add_f32_e32 v4, v64, v4
	v_mov_b32_e32 v64, v60
	v_mov_b32_e32 v65, v52
	v_pk_mul_f32 v[64:65], v[64:65], v[100:101]
	v_mul_f32_e32 v68, v4, v17
	v_fma_f32 v4, v56, v16, v65
	v_add_f32_e32 v4, v64, v4
	v_and_b32_e32 v17, 0xffff0000, v32
	v_lshlrev_b32_e32 v113, 16, v70
	v_and_b32_e32 v119, 0xffff0000, v70
	v_lshlrev_b32_e32 v126, 16, v71
	v_and_b32_e32 v127, 0xffff0000, v71
	v_mov_b32_e32 v70, v61
	v_mov_b32_e32 v71, v57
	v_mul_f32_e32 v69, v4, v105
	v_mov_b32_e32 v4, v17
	v_and_b32_e32 v16, 0xffff0000, v36
	v_pk_mul_f32 v[4:5], v[70:71], v[4:5]
	v_mov_b32_e32 v64, v61
	v_mov_b32_e32 v65, v53
	v_fma_f32 v5, v53, v104, v5
	v_pk_mul_f32 v[64:65], v[64:65], v[16:17]
	v_add_f32_e32 v4, v4, v5
	v_fma_f32 v5, v57, v104, v65
	v_lshlrev_b32_e32 v105, 16, v33
	v_mov_b32_e32 v74, v62
	v_mov_b32_e32 v75, v58
	v_add_f32_e32 v5, v64, v5
	v_mov_b32_e32 v64, v105
	v_mov_b32_e32 v65, v6
	v_pk_mul_f32 v[64:65], v[74:75], v[64:65]
	v_mul_f32_e32 v32, v5, v107
	v_fma_f32 v5, v54, v18, v65
	v_lshlrev_b32_e32 v104, 16, v37
	v_add_f32_e32 v5, v64, v5
	v_mov_b32_e32 v64, v62
	v_mov_b32_e32 v65, v54
	v_pk_mul_f32 v[64:65], v[64:65], v[104:105]
	v_mul_f32_e32 v4, v4, v19
	v_fma_f32 v6, v58, v18, v65
	v_add_f32_e32 v6, v64, v6
	v_and_b32_e32 v19, 0xffff0000, v33
	v_mov_b32_e32 v76, v63
	v_mov_b32_e32 v77, v59
	v_mul_f32_e32 v36, v6, v132
	v_mov_b32_e32 v6, v19
	v_pk_mul_f32 v[6:7], v[76:77], v[6:7]
	v_mul_f32_e32 v5, v5, v21
	v_fma_f32 v7, v55, v106, v7
	v_add_f32_e32 v6, v6, v7
	v_mul_f32_e32 v6, v6, v23
	v_cvt_pk_bf16_f32 v4, v68, v4
	v_and_b32_e32 v18, 0xffff0000, v37
	v_cvt_pk_bf16_f32 v5, v5, v6
	v_mov_b32_e32 v6, v63
	v_mov_b32_e32 v7, v55
	v_pk_mul_f32 v[6:7], v[6:7], v[18:19]
	v_lshlrev_b32_e32 v107, 16, v34
	v_fma_f32 v7, v59, v106, v7
	v_add_f32_e32 v6, v6, v7
	v_mov_b32_e32 v78, v48
	v_mov_b32_e32 v79, v44
	v_mul_f32_e32 v33, v6, v133
	v_mov_b32_e32 v6, v107
	v_mov_b32_e32 v7, v0
	v_pk_mul_f32 v[6:7], v[78:79], v[6:7]
	v_lshlrev_b32_e32 v106, 16, v38
	v_fma_f32 v0, v40, v20, v7
	v_add_f32_e32 v0, v6, v0
	v_mov_b32_e32 v6, v48
	v_mov_b32_e32 v7, v40
	v_pk_mul_f32 v[6:7], v[6:7], v[106:107]
	v_mul_f32_e32 v23, v0, v113
	v_fma_f32 v0, v44, v20, v7
	v_lshlrev_b32_e32 v134, 16, v66
	v_add_f32_e32 v0, v6, v0
	v_and_b32_e32 v21, 0xffff0000, v34
	v_mov_b32_e32 v120, v49
	v_mov_b32_e32 v121, v45
	v_mul_f32_e32 v37, v0, v134
	v_mov_b32_e32 v0, v21
	v_pk_mul_f32 v[0:1], v[120:121], v[0:1]
	v_and_b32_e32 v20, 0xffff0000, v38
	v_fma_f32 v1, v41, v112, v1
	v_add_f32_e32 v0, v0, v1
	v_mul_f32_e32 v0, v0, v119
	v_cvt_pk_bf16_f32 v6, v23, v0
	v_mov_b32_e32 v0, v49
	v_mov_b32_e32 v1, v41
	v_pk_mul_f32 v[0:1], v[0:1], v[20:21]
	v_and_b32_e32 v66, 0xffff0000, v66
	v_fma_f32 v1, v45, v112, v1
	v_add_f32_e32 v0, v0, v1
	v_lshlrev_b32_e32 v113, 16, v35
	v_mov_b32_e32 v122, v50
	v_mov_b32_e32 v123, v46
	v_mul_f32_e32 v34, v0, v66
	v_mov_b32_e32 v0, v113
	v_mov_b32_e32 v1, v2
	v_pk_mul_f32 v[0:1], v[122:123], v[0:1]
	v_lshlrev_b32_e32 v112, 16, v39
	v_fma_f32 v1, v42, v22, v1
	v_add_f32_e32 v0, v0, v1
	v_mul_f32_e32 v7, v0, v126
	v_mov_b32_e32 v0, v50
	v_mov_b32_e32 v1, v42
	v_pk_mul_f32 v[0:1], v[0:1], v[112:113]
	v_and_b32_e32 v23, 0xffff0000, v35
	v_fma_f32 v1, v46, v22, v1
	v_mov_b32_e32 v124, v51
	v_mov_b32_e32 v125, v47
	v_lshlrev_b32_e32 v135, 16, v67
	v_add_f32_e32 v0, v0, v1
	v_mov_b32_e32 v2, v23
	v_mul_f32_e32 v38, v0, v135
	v_pk_mul_f32 v[0:1], v[124:125], v[2:3]
	v_and_b32_e32 v22, 0xffff0000, v39
	v_fma_f32 v1, v43, v118, v1
	v_add_f32_e32 v0, v0, v1
	v_mul_f32_e32 v0, v0, v127
	v_cvt_pk_bf16_f32 v7, v7, v0
	v_mov_b32_e32 v0, v51
	v_mov_b32_e32 v1, v43
	v_pk_mul_f32 v[0:1], v[0:1], v[22:23]
	v_and_b32_e32 v67, 0xffff0000, v67
	v_fma_f32 v1, v47, v118, v1
	v_add_f32_e32 v0, v0, v1
	v_mul_f32_e32 v3, v0, v67
	global_store_dwordx4 v[110:111], v[4:7], off sc1
	v_cvt_pk_bf16_f32 v0, v69, v32
	v_cvt_pk_bf16_f32 v1, v36, v33
	v_cvt_pk_bf16_f32 v2, v37, v34
	v_cvt_pk_bf16_f32 v3, v38, v3
	v_mov_b32_e32 v128, v57
	s_nop 0
	v_lshlrev_b32_e32 v4, 16, v28
	global_store_dwordx4 v[108:109], v[0:3], off sc1
	v_and_b32_e32 v5, 0xffff0000, v28
	v_lshlrev_b32_e32 v6, 16, v29
	v_and_b32_e32 v7, 0xffff0000, v29
	v_lshlrev_b32_e32 v0, 16, v30
	v_and_b32_e32 v1, 0xffff0000, v30
	v_lshlrev_b32_e32 v2, 16, v31
	v_and_b32_e32 v3, 0xffff0000, v31
	v_lshlrev_b32_e32 v28, 16, v24
	v_and_b32_e32 v29, 0xffff0000, v24
	v_lshlrev_b32_e32 v30, 16, v25
	v_and_b32_e32 v31, 0xffff0000, v25
	v_mov_b32_e32 v57, v60
	v_mov_b32_e32 v24, v101
	v_mov_b32_e32 v25, v4
	v_pk_mul_f32 v[24:25], v[56:57], v[24:25]
	v_mov_b32_e32 v60, v128
; __device__ __forceinline__ unsigned cvt_pk_bf16(float lo, float hi) { unsigned r; asm volatile("v_cvt_pk_bf16_f32 %0, %1, %2" : "=v"(r) : "v"(lo), "v"(hi)); return r; }
; __device__ __forceinline__ void conv_block(ArgP a, int layer, int r0, int lane, const bf16* U, bf16* BG) {
;     ...
;         for (int k = 0; k < 4; ++k) {
;             float u0[8], bg[8], y[8];
;             { const u32x4 w = uw[k]; u0[0] = bflo(w.x); u0[1] = bfhi(w.x); u0[2] = bflo(w.y); u0[3] = bfhi(w.y); u0[4] = bflo(w.z); u0[5] = bfhi(w.z); u0[6] = bflo(w.w); u0[7] = bfhi(w.w); }
;             { const u32x4 w = bw[k]; bg[0] = bflo(w.x); bg[1] = bfhi(w.x); bg[2] = bflo(w.y); bg[3] = bfhi(w.y); bg[4] = bflo(w.z); bg[5] = bfhi(w.z); bg[6] = bflo(w.w); bg[7] = bfhi(w.w); }
; #pragma unroll
;             for (int x = 0; x < 8; ++x) y[x] = bg[x] * (w0[x] * p2[x] + w1[x] * p1[x] + w2[x] * u0[x]);
;             u32x4 wv; wv.x = cvt_pk_bf16(y[0], y[1]); wv.y = cvt_pk_bf16(y[2], y[3]); wv.z = cvt_pk_bf16(y[4], y[5]); wv.w = cvt_pk_bf16(y[6], y[7]);
;             *(u32x4*)(BG + (size_t)(r0 + k) * DM + col) = wv;
;             if (st_out && k >= 2) { float* so = st_out + (size_t)(k - 2) * DM + col; *(f32x4*)so = (f32x4){u0[0], u0[1], u0[2], u0[3]}; *(f32x4*)(so + 4) = (f32x4){u0[4], u0[5], u0[6], u0[7]}; }
; #pragma unroll
;             for (int x = 0; x < 8; ++x) { p2[x] = p1[x]; p1[x] = u0[x]; }
;         }
; __device__ __forceinline__ void mixer_phase(ArgP a, LAS unsigned char* lds, int layer, int G) {
;     ...
;         for (int blk = oi * NWAVES + wave; blk < M_REAL / 4; blk += n_other * NWAVES) conv_block(a, layer, blk * 4, lane, Ub, BGb);
;         asm volatile("s_waitcnt vmcnt(0)" ::: "memory"); __syncthreads();
;         if (tid_ == 0) { __builtin_amdgcn_fence(__ATOMIC_RELEASE, "agent"); asm volatile("s_waitcnt vmcnt(0)" ::: "memory"); (void)__hip_atomic_fetch_add(cnt, 1u, __ATOMIC_RELAXED, __HIP_MEMORY_SCOPE_AGENT); }
	v_fma_f32 v24, v52, v100, v24
	v_add_f32_e32 v24, v24, v25
	v_mul_f32_e32 v28, v24, v28
	v_mov_b32_e32 v24, v17
	v_mov_b32_e32 v25, v5
	v_pk_mul_f32 v[24:25], v[60:61], v[24:25]
	v_mov_b32_e32 v129, v59
	v_fma_f32 v17, v53, v16, v24
	v_add_f32_e32 v17, v17, v25
	v_mov_b32_e32 v59, v62
	v_mov_b32_e32 v24, v105
	v_mov_b32_e32 v25, v6
	v_pk_mul_f32 v[24:25], v[58:59], v[24:25]
	v_mul_f32_e32 v17, v17, v29
	v_fma_f32 v24, v54, v104, v24
	v_add_f32_e32 v24, v24, v25
	v_mul_f32_e32 v29, v24, v30
	v_mov_b32_e32 v62, v129
	v_mov_b32_e32 v24, v19
	v_mov_b32_e32 v25, v7
	v_pk_mul_f32 v[24:25], v[62:63], v[24:25]
	v_mov_b32_e32 v130, v45
	v_fma_f32 v19, v55, v18, v24
	v_add_f32_e32 v19, v19, v25
	v_mov_b32_e32 v45, v48
	v_mov_b32_e32 v24, v107
	v_mov_b32_e32 v25, v0
	v_pk_mul_f32 v[24:25], v[44:45], v[24:25]
	v_lshlrev_b32_e32 v32, 16, v26
	v_fma_f32 v24, v40, v106, v24
	v_add_f32_e32 v24, v24, v25
	v_mul_f32_e32 v30, v24, v32
	v_mov_b32_e32 v48, v130
	v_mov_b32_e32 v24, v21
	v_mov_b32_e32 v25, v1
	v_pk_mul_f32 v[24:25], v[48:49], v[24:25]
	v_mov_b32_e32 v131, v47
	v_fma_f32 v21, v41, v20, v24
	v_add_f32_e32 v21, v21, v25
	v_mov_b32_e32 v47, v50
	v_mov_b32_e32 v24, v113
	v_mov_b32_e32 v25, v2
	v_pk_mul_f32 v[24:25], v[46:47], v[24:25]
	v_lshlrev_b32_e32 v33, 16, v27
	v_fma_f32 v24, v42, v112, v24
	v_add_f32_e32 v24, v24, v25
	v_mul_f32_e32 v19, v19, v31
	v_mul_f32_e32 v31, v24, v33
	v_mov_b32_e32 v50, v131
	v_mov_b32_e32 v24, v23
	v_mov_b32_e32 v25, v3
	v_pk_mul_f32 v[24:25], v[50:51], v[24:25]
	v_lshl_add_u64 v[72:73], v[188:189], 2, v[82:83]
	v_fma_f32 v23, v43, v22, v24
	v_and_b32_e32 v26, 0xffff0000, v26
	v_and_b32_e32 v27, 0xffff0000, v27
	v_add_f32_e32 v23, v23, v25
	v_mul_f32_e32 v21, v21, v26
	v_mul_f32_e32 v23, v23, v27
	v_cvt_pk_bf16_f32 v24, v28, v17
	v_cvt_pk_bf16_f32 v25, v29, v19
	v_cvt_pk_bf16_f32 v26, v30, v21
	v_cvt_pk_bf16_f32 v27, v31, v23
	global_store_dwordx4 v[102:103], v[24:27], off sc1
	s_and_saveexec_b64 s[26:27], s[6:7]
	s_cbranch_execz .LBB0_503
	global_store_dwordx4 v[72:73], v[4:7], off
	global_store_dwordx4 v[72:73], v[0:3], off offset:16
.LBB0_503:
	s_or_b64 exec, exec, s[26:27]
	v_lshlrev_b32_e32 v101, 16, v12
	v_and_b32_e32 v17, 0xffff0000, v12
	v_lshlrev_b32_e32 v105, 16, v13
	v_and_b32_e32 v19, 0xffff0000, v13
	v_lshlrev_b32_e32 v107, 16, v14
	v_and_b32_e32 v21, 0xffff0000, v14
	v_lshlrev_b32_e32 v113, 16, v15
	v_and_b32_e32 v23, 0xffff0000, v15
	v_lshlrev_b32_e32 v12, 16, v8
	v_and_b32_e32 v13, 0xffff0000, v8
	v_lshlrev_b32_e32 v14, 16, v9
	v_and_b32_e32 v15, 0xffff0000, v9
	v_pk_mul_f32 v[8:9], v[56:57], v[100:101]
	v_lshlrev_b32_e32 v24, 16, v10
	v_fma_f32 v8, v52, v4, v8
	v_add_f32_e32 v8, v8, v9
	v_mul_f32_e32 v12, v8, v12
	v_pk_mul_f32 v[8:9], v[60:61], v[16:17]
	v_and_b32_e32 v10, 0xffff0000, v10
	v_fma_f32 v8, v53, v5, v8
	v_add_f32_e32 v8, v8, v9
	v_mul_f32_e32 v13, v8, v13
	v_pk_mul_f32 v[8:9], v[58:59], v[104:105]
	v_lshlrev_b32_e32 v25, 16, v11
	v_fma_f32 v8, v54, v6, v8
	v_add_f32_e32 v8, v8, v9
	v_mul_f32_e32 v14, v8, v14
	v_pk_mul_f32 v[8:9], v[62:63], v[18:19]
	v_and_b32_e32 v11, 0xffff0000, v11
	v_fma_f32 v8, v55, v7, v8
	v_add_f32_e32 v8, v8, v9
	v_mul_f32_e32 v15, v8, v15
	v_pk_mul_f32 v[8:9], v[44:45], v[106:107]
	s_nop 0
	v_fma_f32 v8, v40, v0, v8
	v_add_f32_e32 v8, v8, v9
	v_mul_f32_e32 v16, v8, v24
	v_pk_mul_f32 v[8:9], v[48:49], v[20:21]
	s_nop 0
	v_fma_f32 v8, v41, v1, v8
	v_add_f32_e32 v8, v8, v9
	v_mul_f32_e32 v10, v8, v10
	v_pk_mul_f32 v[8:9], v[46:47], v[112:113]
	s_nop 0
	v_fma_f32 v8, v42, v2, v8
	v_add_f32_e32 v8, v8, v9
	v_mul_f32_e32 v18, v8, v25
	v_pk_mul_f32 v[8:9], v[50:51], v[22:23]
	s_nop 0
	v_fma_f32 v8, v43, v3, v8
	v_add_f32_e32 v8, v8, v9
	v_mul_f32_e32 v11, v8, v11
	v_cvt_pk_bf16_f32 v8, v12, v13
	v_cvt_pk_bf16_f32 v9, v14, v15
	v_cvt_pk_bf16_f32 v10, v16, v10
	v_cvt_pk_bf16_f32 v11, v18, v11
	global_store_dwordx4 v[98:99], v[8:11], off sc1
	s_and_saveexec_b64 s[26:27], s[6:7]
	s_cbranch_execz .LBB0_490
	v_add_co_u32_e32 v8, vcc, 0x1000, v72
	v_mov_b32_e32 v16, v101
	v_mov_b32_e32 v18, v105
	v_addc_co_u32_e32 v9, vcc, 0, v73, vcc
	v_mov_b32_e32 v20, v107
	v_mov_b32_e32 v22, v113
	global_store_dwordx4 v[8:9], v[16:19], off
	global_store_dwordx4 v[8:9], v[20:23], off offset:16
	s_branch .LBB0_490
.LBB0_505:
	s_or_b64 exec, exec, s[14:15]
	v_readlane_b32 s0, v255, 4
	v_readlane_b32 s1, v255, 5
	s_mov_b32 s5, s1
	v_readlane_b32 s0, v255, 6
	v_readlane_b32 s1, v255, 7
	s_mov_b32 s1, s5
	s_lshl_b32 s4, s0, 6
	v_writelane_b32 v255, s0, 4
	s_waitcnt vmcnt(0)
	s_barrier
	s_nop 0
	v_writelane_b32 v255, s1, 5
	s_lshl_b64 s[0:1], s[4:5], 2
	v_readlane_b32 s4, v255, 15
	v_readlane_b32 s5, v255, 16
	s_add_u32 s0, s4, s0
	s_addc_u32 s1, s5, s1
	s_add_u32 s4, s0, 0x183800
	s_addc_u32 s5, s1, 0
	v_cmp_eq_u32_e64 s[0:1], 0, v140
	s_and_saveexec_b64 s[6:7], s[0:1]
	s_cbranch_execz .LBB0_508
	s_mov_b64 s[8:9], exec
	v_mbcnt_lo_u32_b32 v0, s8, 0
	s_waitcnt vmcnt(0)
	s_waitcnt vmcnt(0)
	v_mbcnt_hi_u32_b32 v0, s9, v0
	v_cmp_eq_u32_e32 vcc, 0, v0
	s_and_b64 s[14:15], exec, vcc
	s_mov_b64 exec, s[14:15]
	s_cbranch_execz .LBB0_508
	s_bcnt1_i32_b64 s8, s[8:9]
	v_mov_b32_e32 v0, s8
	global_atomic_add v189, v0, s[4:5]

; #define PG8_BAR __builtin_amdgcn_s_barrier()
; template <class Epi, class Sched, bool ALIGN_EPI = false, bool SP2 = false>
; __device__ __forceinline__ void gemm_phase(PG8_LAS unsigned char* lds, const Gemm g, const Sched& S, const Epi& E) {
;     ...
;         if constexpr (!Epi::AFTER_DRAIN) { E(acc, cur, wr, wc, fr, fq); S.done(cur); }
;         if (!has_next) break;
; #pragma unroll
;         for (int a = 0; a < 2; ++a)
; #pragma unroll
;             for (int b = 0; b < 2; ++b)
; #pragma unroll
;                 for (int m = 0; m < 4; ++m)
; #pragma unroll
;                     for (int n = 0; n < 2; ++n) acc[a][b][m][n] = zero4_;
;         cur = nxt; cA = nA; cB = nB; ++ui;
;         if constexpr (ALIGN_EPI) { if (wr == 1) PG8_BAR; }
.Lp3b_fx:
	s_mov_b64 s[14:15], -1
	v_readlane_b32 s16, v254, 44
	v_readlane_b32 s17, v254, 45
	s_mov_b64 s[18:19], 0x40000
	v_readlane_b32 s38, v254, 55
	v_readlane_b32 s39, v254, 56
	s_andn2_b64 vcc, exec, s[4:5]
	s_cbranch_vccnz .LBB0_719
	s_andn2_b64 vcc, exec, s[0:1]
	s_cbranch_vccnz .LBB0_718
	s_barrier
	s_branch .LBB0_718
